# hyena main-unit prologue: 24 halo loads issued back to back with one wait (each had its own vmcnt(0))
# speedup vs baseline: 1.0124x; 1.0047x over previous
.LBB0_1353:
	s_or_b64 exec, exec, s[16:17]
	v_readlane_b32 s4, v251, 20
	s_waitcnt lgkmcnt(0)
	s_barrier
	v_mov_b32_e32 v2, s4
	ds_read_b32 v2, v2
	s_mov_b64 s[14:15], -1
	s_waitcnt lgkmcnt(0)
	v_cmp_le_i32_e32 vcc, s29, v2
	v_readfirstlane_b32 s9, v2
	s_cbranch_vccnz .LBB0_1348
	s_cmpk_gt_i32 s9, 0x107
	s_cbranch_scc0 .LBB0_1549
	s_add_i32 s4, s9, 0xfffffef8
	s_and_b32 s5, s4, 0x100
	s_or_b32 s6, s5, 0x4000
	s_lshl_b32 s5, s4, 5
	s_and_b32 s12, s4, 0xff
	s_and_b32 s7, s5, 0x2000
	s_cmpk_lt_u32 s4, 0x200
	s_cselect_b64 s[18:19], -1, 0
	s_and_b64 s[4:5], s[18:19], exec
	s_movk_i32 s4, 0x2000
	s_cselect_b32 s52, s4, 0x100
	s_mul_i32 s4, s12, 0x8400
	v_mov_b32_e32 v59, v0
	v_writelane_b32 v251, s9, 58
	s_cselect_b32 s6, s7, s6
	s_lshl_b32 s4, s4, 1
	v_readlane_b32 s8, v252, 43
	v_readlane_b32 s9, v252, 44
	v_writelane_b32 v251, s4, 59
	s_add_u32 s7, s8, s4
	s_load_dwordx2 s[4:5], s[0:1], 0x98
	s_addc_u32 s8, s9, 0
	s_lshl_b32 s6, s6, 1
	v_writelane_b32 v251, s6, 60
	s_add_u32 s16, s7, s6
	v_readlane_b32 s10, v251, 39
	s_addc_u32 s17, s8, 0
	s_mul_i32 s6, s10, 0x4800
	s_waitcnt lgkmcnt(0)
	s_add_u32 s4, s4, s6
	s_load_dwordx2 s[6:7], s[0:1], 0xa0
	s_mul_hi_u32 s8, s10, 0x4800
	s_addc_u32 s5, s5, s8
	s_lshl_b32 s8, s12, 3
	s_add_u32 s44, s4, s8
	s_addc_u32 s45, s5, 0
	s_mul_i32 s4, s10, 0x1800
	s_waitcnt lgkmcnt(0)
	s_add_u32 s4, s6, s4
	s_mul_hi_u32 s5, s10, 0x1800
	v_mov_b32_e32 v2, s44
	s_addc_u32 s5, s7, s5
	v_add_co_u32_e32 v6, vcc, 0x1000, v2
	v_mov_b32_e32 v9, s45
	s_add_u32 s26, s4, s8
	v_addc_co_u32_e32 v7, vcc, 0, v9, vcc
	s_addc_u32 s27, s5, 0
	v_mov_b64_e32 v[4:5], s[44:45]
	v_add_co_u32_e32 v8, vcc, 0x3000, v2
	v_lshlrev_b32_e32 v52, 3, v59
	s_nop 0
	v_addc_co_u32_e32 v9, vcc, 0, v9, vcc
	flat_load_dword v89, v[4:5]
	flat_load_dword v83, v[6:7] offset:2048
	flat_load_dword v85, v[8:9]
	v_mov_b64_e32 v[4:5], s[26:27]
	flat_load_dword v87, v[4:5]
	v_cmp_gt_i32_e64 s[34:35], s52, v52
	v_mov_b32_e32 v64, 0
	v_mov_b32_e32 v43, 0
	v_ashrrev_i32_e32 v53, 31, v52
	v_mov_b32_e32 v42, 0
	v_mov_b32_e32 v41, 0
	v_mov_b32_e32 v40, 0
	v_mov_b32_e32 v65, 0
	v_readlane_b32 s11, v251, 40
	s_and_saveexec_b64 s[38:39], s[34:35]
	s_cbranch_execz .LBB0_1361
	v_lshl_add_u64 v[4:5], v[52:53], 1, s[16:17]
	global_load_dwordx4 v[40:43], v[4:5], off
	v_cmp_lt_i32_e32 vcc, 0, v52
	v_mov_b32_e32 v65, 0
	v_mov_b32_e32 v64, 0
	s_and_saveexec_b64 s[14:15], vcc
	s_cbranch_execz .LBB0_1358
	v_mov_b32_e32 v2, v52
	v_lshl_add_u64 v[6:7], v[2:3], 1, s[16:17]
	global_load_ushort v64, v[6:7], off offset:-2
.LBB0_1358:
	s_or_b64 exec, exec, s[14:15]
	v_add_u32_e32 v2, 8, v52
	v_cmp_gt_i32_e32 vcc, s52, v2
	s_and_saveexec_b64 s[14:15], vcc
	s_cbranch_execz .LBB0_1360
	global_load_ushort v65, v[4:5], off offset:16

.LBB0_1361:
	s_or_b64 exec, exec, s[38:39]
	s_lshl_b32 s4, s12, 1
	v_add_u32_e32 v54, 0x1000, v52
	v_writelane_b32 v251, s4, 61
	v_cmp_gt_i32_e64 s[6:7], s52, v54
	v_mov_b32_e32 v82, 0
	v_mov_b32_e32 v39, 0
	v_ashrrev_i32_e32 v55, 31, v54
	v_mov_b32_e32 v38, 0
	v_mov_b32_e32 v37, 0
	v_mov_b32_e32 v36, 0
	v_mov_b32_e32 v90, 0
	s_and_saveexec_b64 s[38:39], s[6:7]
	s_cbranch_execz .LBB0_1367
	v_lshl_add_u64 v[4:5], v[54:55], 1, s[16:17]
	global_load_dwordx4 v[36:39], v[4:5], off
	v_cmp_lt_i32_e32 vcc, 0, v54
	v_mov_b32_e32 v90, 0
	v_mov_b32_e32 v82, 0
	s_and_saveexec_b64 s[14:15], vcc
	s_cbranch_execz .LBB0_1364
	v_mov_b32_e32 v2, v54
	v_lshl_add_u64 v[4:5], v[2:3], 1, s[16:17]
	global_load_ushort v82, v[4:5], off offset:-2
.LBB0_1364:
	s_or_b64 exec, exec, s[14:15]
	v_add_u32_e32 v4, 0x1008, v52
	v_cmp_gt_i32_e32 vcc, s52, v4
	s_and_saveexec_b64 s[14:15], vcc
	s_cbranch_execz .LBB0_1366
	v_ashrrev_i32_e32 v5, 31, v4
	v_lshl_add_u64 v[4:5], v[4:5], 1, s[16:17]
	global_load_ushort v90, v[4:5], off

.LBB0_1367:
	s_or_b64 exec, exec, s[38:39]
	v_mov_b32_e32 v2, s44
	v_add_co_u32_e32 v6, vcc, 0x1000, v2
	v_mov_b32_e32 v9, s45
	s_nop 0
	v_addc_co_u32_e32 v7, vcc, 0, v9, vcc
	v_mov_b64_e32 v[4:5], s[44:45]
	v_add_co_u32_e32 v8, vcc, 0x3000, v2
	s_add_u32 s38, s16, 0x8400
	s_nop 0
	v_addc_co_u32_e32 v9, vcc, 0, v9, vcc
	flat_load_dword v91, v[4:5] offset:4
	flat_load_dword v96, v[6:7] offset:2052
	flat_load_dword v97, v[8:9] offset:4
	v_mov_b64_e32 v[4:5], s[26:27]
	flat_load_dword v108, v[4:5] offset:4
	s_addc_u32 s39, s17, 0
	v_mov_b32_e32 v67, 0
	v_mov_b32_e32 v51, 0
	v_mov_b32_e32 v50, 0
	v_mov_b32_e32 v49, 0
	v_mov_b32_e32 v48, 0
	v_mov_b32_e32 v80, 0
	s_and_saveexec_b64 s[46:47], s[34:35]
	s_cbranch_execz .LBB0_1373
	v_lshl_add_u64 v[4:5], v[52:53], 1, s[38:39]
	global_load_dwordx4 v[48:51], v[4:5], off
	v_cmp_lt_i32_e32 vcc, 0, v52
	v_mov_b32_e32 v80, 0
	v_mov_b32_e32 v67, 0
	s_and_saveexec_b64 s[14:15], vcc
	s_cbranch_execz .LBB0_1370
	v_mov_b32_e32 v2, v52
	v_lshl_add_u64 v[6:7], v[2:3], 1, s[38:39]
	global_load_ushort v67, v[6:7], off offset:-2
.LBB0_1370:
	s_or_b64 exec, exec, s[14:15]
	v_add_u32_e32 v2, 8, v52
	v_cmp_gt_i32_e32 vcc, s52, v2
	s_and_saveexec_b64 s[14:15], vcc
	s_cbranch_execz .LBB0_1372
	global_load_ushort v80, v[4:5], off offset:16

.LBB0_1373:
	s_or_b64 exec, exec, s[46:47]
	v_mov_b32_e32 v99, 0
	v_mov_b32_e32 v47, 0
	v_mov_b32_e32 v46, 0
	v_mov_b32_e32 v45, 0
	v_mov_b32_e32 v44, 0
	v_mov_b32_e32 v98, 0
	s_and_saveexec_b64 s[46:47], s[6:7]
	s_cbranch_execz .LBB0_1379
	v_lshl_add_u64 v[4:5], v[54:55], 1, s[38:39]
	global_load_dwordx4 v[44:47], v[4:5], off
	v_cmp_lt_i32_e32 vcc, 0, v54
	v_mov_b32_e32 v98, 0
	v_mov_b32_e32 v99, 0
	s_and_saveexec_b64 s[14:15], vcc
	s_cbranch_execz .LBB0_1376
	v_mov_b32_e32 v2, v54
	v_lshl_add_u64 v[4:5], v[2:3], 1, s[38:39]
	global_load_ushort v99, v[4:5], off offset:-2
.LBB0_1376:
	s_or_b64 exec, exec, s[14:15]
	v_add_u32_e32 v4, 0x1008, v52
	v_cmp_gt_i32_e32 vcc, s52, v4
	s_and_saveexec_b64 s[14:15], vcc
	s_cbranch_execz .LBB0_1378
	v_ashrrev_i32_e32 v5, 31, v4
	v_lshl_add_u64 v[4:5], v[4:5], 1, s[38:39]
	global_load_ushort v98, v[4:5], off

.LBB0_1379:
	s_or_b64 exec, exec, s[46:47]
	v_mov_b32_e32 v2, s44
	v_add_co_u32_e32 v6, vcc, 0x2000, v2
	v_mov_b32_e32 v9, s45
	s_nop 0
	v_addc_co_u32_e32 v7, vcc, 0, v9, vcc
	v_mov_b64_e32 v[4:5], s[44:45]
	v_add_co_u32_e32 v8, vcc, 0x3000, v2
	s_add_u32 s38, s16, 0x1080000
	s_nop 0
	v_addc_co_u32_e32 v9, vcc, 0, v9, vcc
	flat_load_dword v107, v[4:5] offset:2048
	flat_load_dword v100, v[6:7]
	flat_load_dword v101, v[8:9] offset:2048
	v_mov_b64_e32 v[4:5], s[26:27]
	flat_load_dword v154, v[4:5] offset:2048
	s_addc_u32 s39, s17, 0
	v_mov_b32_e32 v113, 0
	v_mov_b32_e32 v31, 0
	v_mov_b32_e32 v30, 0
	v_mov_b32_e32 v29, 0
	v_mov_b32_e32 v28, 0
	v_mov_b32_e32 v112, 0
	s_and_saveexec_b64 s[46:47], s[34:35]
	s_cbranch_execz .LBB0_1385
	v_lshl_add_u64 v[4:5], v[52:53], 1, s[38:39]
	global_load_dwordx4 v[28:31], v[4:5], off
	v_cmp_lt_i32_e32 vcc, 0, v52
	v_mov_b32_e32 v112, 0
	v_mov_b32_e32 v113, 0
	s_and_saveexec_b64 s[14:15], vcc
	s_cbranch_execz .LBB0_1382
	v_mov_b32_e32 v2, v52
	v_lshl_add_u64 v[6:7], v[2:3], 1, s[38:39]
	global_load_ushort v113, v[6:7], off offset:-2
.LBB0_1382:
	s_or_b64 exec, exec, s[14:15]
	v_add_u32_e32 v2, 8, v52
	v_cmp_gt_i32_e32 vcc, s52, v2
	s_and_saveexec_b64 s[14:15], vcc
	s_cbranch_execz .LBB0_1384
	global_load_ushort v112, v[4:5], off offset:16

.LBB0_1385:
	s_or_b64 exec, exec, s[46:47]
	v_mov_b32_e32 v103, 0
	v_mov_b32_e32 v23, 0
	v_mov_b32_e32 v22, 0
	v_mov_b32_e32 v21, 0
	v_mov_b32_e32 v20, 0
	v_mov_b32_e32 v102, 0
	s_and_saveexec_b64 s[46:47], s[6:7]
	s_cbranch_execz .LBB0_1391
	v_lshl_add_u64 v[4:5], v[54:55], 1, s[38:39]
	global_load_dwordx4 v[20:23], v[4:5], off
	v_cmp_lt_i32_e32 vcc, 0, v54
	v_mov_b32_e32 v102, 0
	v_mov_b32_e32 v103, 0
	s_and_saveexec_b64 s[14:15], vcc
	s_cbranch_execz .LBB0_1388
	v_mov_b32_e32 v2, v54
	v_lshl_add_u64 v[4:5], v[2:3], 1, s[38:39]
	global_load_ushort v103, v[4:5], off offset:-2
.LBB0_1388:
	s_or_b64 exec, exec, s[14:15]
	v_add_u32_e32 v4, 0x1008, v52
	v_cmp_gt_i32_e32 vcc, s52, v4
	s_and_saveexec_b64 s[14:15], vcc
	s_cbranch_execz .LBB0_1390
	v_ashrrev_i32_e32 v5, 31, v4
	v_lshl_add_u64 v[4:5], v[4:5], 1, s[38:39]
	global_load_ushort v102, v[4:5], off

.LBB0_1391:
	s_or_b64 exec, exec, s[46:47]
	v_mov_b32_e32 v2, s44
	v_add_co_u32_e32 v6, vcc, 0x2000, v2
	v_mov_b32_e32 v9, s45
	s_nop 0
	v_addc_co_u32_e32 v7, vcc, 0, v9, vcc
	v_mov_b64_e32 v[4:5], s[44:45]
	v_add_co_u32_e32 v8, vcc, 0x3000, v2
	s_add_u32 s38, s16, 0x1088400
	s_nop 0
	v_addc_co_u32_e32 v9, vcc, 0, v9, vcc
	flat_load_dword v156, v[4:5] offset:2052
	flat_load_dword v104, v[6:7] offset:4
	flat_load_dword v105, v[8:9] offset:2052
	v_mov_b64_e32 v[4:5], s[26:27]
	flat_load_dword v155, v[4:5] offset:2052
	s_addc_u32 s39, s17, 0
	v_mov_b32_e32 v115, 0
	v_mov_b32_e32 v35, 0
	v_mov_b32_e32 v34, 0
	v_mov_b32_e32 v33, 0
	v_mov_b32_e32 v32, 0
	v_mov_b32_e32 v114, 0
	s_and_saveexec_b64 s[46:47], s[34:35]
	s_cbranch_execz .LBB0_1397
	v_lshl_add_u64 v[4:5], v[52:53], 1, s[38:39]
	global_load_dwordx4 v[32:35], v[4:5], off
	v_cmp_lt_i32_e32 vcc, 0, v52
	v_mov_b32_e32 v114, 0
	v_mov_b32_e32 v115, 0
	s_and_saveexec_b64 s[14:15], vcc
	s_cbranch_execz .LBB0_1394
	v_mov_b32_e32 v2, v52
	v_lshl_add_u64 v[6:7], v[2:3], 1, s[38:39]
	global_load_ushort v115, v[6:7], off offset:-2
.LBB0_1394:
	s_or_b64 exec, exec, s[14:15]
	v_add_u32_e32 v2, 8, v52
	v_cmp_gt_i32_e32 vcc, s52, v2
	s_and_saveexec_b64 s[14:15], vcc
	s_cbranch_execz .LBB0_1396
	global_load_ushort v114, v[4:5], off offset:16

.LBB0_1397:
	s_or_b64 exec, exec, s[46:47]
	v_mov_b32_e32 v157, 0
	v_mov_b32_e32 v27, 0
	v_mov_b32_e32 v26, 0
	v_mov_b32_e32 v25, 0
	v_mov_b32_e32 v24, 0
	v_mov_b32_e32 v106, 0
	s_and_saveexec_b64 s[46:47], s[6:7]
	s_cbranch_execz .LBB0_1403
	v_lshl_add_u64 v[4:5], v[54:55], 1, s[38:39]
	global_load_dwordx4 v[24:27], v[4:5], off
	v_cmp_lt_i32_e32 vcc, 0, v54
	v_mov_b32_e32 v106, 0
	v_mov_b32_e32 v157, 0
	s_and_saveexec_b64 s[14:15], vcc
	s_cbranch_execz .LBB0_1400
	v_mov_b32_e32 v2, v54
	v_lshl_add_u64 v[4:5], v[2:3], 1, s[38:39]
	global_load_ushort v157, v[4:5], off offset:-2
.LBB0_1400:
	s_or_b64 exec, exec, s[14:15]
	v_add_u32_e32 v4, 0x1008, v52
	v_cmp_gt_i32_e32 vcc, s52, v4
	s_and_saveexec_b64 s[14:15], vcc
	s_cbranch_execz .LBB0_1402
	v_ashrrev_i32_e32 v5, 31, v4
	v_lshl_add_u64 v[4:5], v[4:5], 1, s[38:39]
	global_load_ushort v106, v[4:5], off

.LBB0_1403:
	s_or_b64 exec, exec, s[46:47]
	v_mov_b32_e32 v2, s44
	v_add_co_u32_e32 v4, vcc, 0x1000, v2
	v_mov_b32_e32 v9, s45
	s_nop 0
	v_addc_co_u32_e32 v5, vcc, 0, v9, vcc
	v_add_co_u32_e32 v6, vcc, 0x2000, v2
	s_add_u32 s38, s16, 0x2100000
	s_nop 0
	v_addc_co_u32_e32 v7, vcc, 0, v9, vcc
	v_add_co_u32_e32 v8, vcc, 0x4000, v2
	v_mov_b32_e32 v2, s26
	s_nop 0
	v_addc_co_u32_e32 v9, vcc, 0, v9, vcc
	flat_load_dword v79, v[4:5]
	flat_load_dword v56, v[6:7] offset:2048
	flat_load_dword v57, v[8:9]
	v_add_co_u32_e32 v4, vcc, 0x1000, v2
	v_mov_b32_e32 v2, s27
	s_nop 0
	v_addc_co_u32_e32 v5, vcc, 0, v2, vcc
	flat_load_dword v146, v[4:5]
	s_addc_u32 s39, s17, 0
	v_mov_b32_e32 v93, 0
	v_mov_b32_e32 v15, 0
	v_mov_b32_e32 v14, 0
	v_mov_b32_e32 v13, 0
	v_mov_b32_e32 v12, 0
	v_mov_b32_e32 v92, 0
	s_and_saveexec_b64 s[46:47], s[34:35]
	s_cbranch_execz .LBB0_1409
	v_lshl_add_u64 v[4:5], v[52:53], 1, s[38:39]
	global_load_dwordx4 v[12:15], v[4:5], off
	v_cmp_lt_i32_e32 vcc, 0, v52
	v_mov_b32_e32 v92, 0
	v_mov_b32_e32 v93, 0
	s_and_saveexec_b64 s[14:15], vcc
	s_cbranch_execz .LBB0_1406
	v_mov_b32_e32 v2, v52
	v_lshl_add_u64 v[6:7], v[2:3], 1, s[38:39]
	global_load_ushort v93, v[6:7], off offset:-2
.LBB0_1406:
	s_or_b64 exec, exec, s[14:15]
	v_add_u32_e32 v2, 8, v52
	v_cmp_gt_i32_e32 vcc, s52, v2
	s_and_saveexec_b64 s[14:15], vcc
	s_cbranch_execz .LBB0_1408
	global_load_ushort v92, v[4:5], off offset:16

.LBB0_1409:
	s_or_b64 exec, exec, s[46:47]
	v_mov_b32_e32 v149, 0
	v_mov_b32_e32 v7, 0
	v_mov_b32_e32 v6, 0
	v_mov_b32_e32 v5, 0
	v_mov_b32_e32 v4, 0
	v_mov_b32_e32 v58, 0
	s_and_saveexec_b64 s[46:47], s[6:7]
	s_cbranch_execz .LBB0_1415
	v_lshl_add_u64 v[4:5], v[54:55], 1, s[38:39]
	global_load_dwordx4 v[4:7], v[4:5], off
	v_cmp_lt_i32_e32 vcc, 0, v54
	v_mov_b32_e32 v58, 0
	v_mov_b32_e32 v149, 0
	s_and_saveexec_b64 s[14:15], vcc
	s_cbranch_execz .LBB0_1412
	v_mov_b32_e32 v2, v54
	v_lshl_add_u64 v[8:9], v[2:3], 1, s[38:39]
	global_load_ushort v149, v[8:9], off offset:-2
.LBB0_1412:
	s_or_b64 exec, exec, s[14:15]
	v_add_u32_e32 v8, 0x1008, v52
	v_cmp_gt_i32_e32 vcc, s52, v8
	s_and_saveexec_b64 s[14:15], vcc
	s_cbranch_execz .LBB0_1414
	v_ashrrev_i32_e32 v9, 31, v8
	v_lshl_add_u64 v[8:9], v[8:9], 1, s[38:39]
	global_load_ushort v58, v[8:9], off

.LBB0_1415:
	s_or_b64 exec, exec, s[46:47]
	v_mov_b32_e32 v2, s44
	v_add_co_u32_e32 v8, vcc, 0x1000, v2
	v_mov_b32_e32 v17, s45
	s_nop 0
	v_addc_co_u32_e32 v9, vcc, 0, v17, vcc
	v_add_co_u32_e32 v10, vcc, 0x2000, v2
	s_add_u32 s16, s16, 0x2108400
	s_nop 0
	v_addc_co_u32_e32 v11, vcc, 0, v17, vcc
	v_add_co_u32_e32 v16, vcc, 0x4000, v2
	v_mov_b32_e32 v2, s26
	s_nop 0
	v_addc_co_u32_e32 v17, vcc, 0, v17, vcc
	flat_load_dword v147, v[8:9] offset:4
	flat_load_dword v60, v[10:11] offset:2052
	flat_load_dword v61, v[16:17] offset:4
	v_add_co_u32_e32 v8, vcc, 0x1000, v2
	v_mov_b32_e32 v2, s27
	s_nop 0
	v_addc_co_u32_e32 v9, vcc, 0, v2, vcc
	flat_load_dword v148, v[8:9] offset:4
	s_addc_u32 s17, s17, 0
	v_mov_b32_e32 v95, 0
	v_mov_b32_e32 v19, 0
	v_mov_b32_e32 v18, 0
	v_mov_b32_e32 v17, 0
	v_mov_b32_e32 v16, 0
	v_mov_b32_e32 v94, 0
	s_and_saveexec_b64 s[26:27], s[34:35]
	s_cbranch_execz .LBB0_1421
	v_lshl_add_u64 v[8:9], v[52:53], 1, s[16:17]
	global_load_dwordx4 v[16:19], v[8:9], off
	v_cmp_lt_i32_e32 vcc, 0, v52
	v_mov_b32_e32 v94, 0
	v_mov_b32_e32 v95, 0
	s_and_saveexec_b64 s[14:15], vcc
	s_cbranch_execz .LBB0_1418
	v_mov_b32_e32 v2, v52
	v_lshl_add_u64 v[10:11], v[2:3], 1, s[16:17]
	global_load_ushort v95, v[10:11], off offset:-2
.LBB0_1418:
	s_or_b64 exec, exec, s[14:15]
	v_add_u32_e32 v2, 8, v52
	v_cmp_gt_i32_e32 vcc, s52, v2
	s_and_saveexec_b64 s[14:15], vcc
	s_cbranch_execz .LBB0_1420
	global_load_ushort v94, v[8:9], off offset:16

.LBB0_1421:
	s_or_b64 exec, exec, s[26:27]
	v_mov_b32_e32 v150, 0
	v_mov_b32_e32 v11, 0
	v_mov_b32_e32 v10, 0
	v_mov_b32_e32 v9, 0
	v_mov_b32_e32 v8, 0
	v_mov_b32_e32 v78, 0
	s_and_saveexec_b64 s[26:27], s[6:7]
	s_cbranch_execz .LBB0_1427
	v_lshl_add_u64 v[8:9], v[54:55], 1, s[16:17]
	global_load_dwordx4 v[8:11], v[8:9], off
	v_cmp_lt_i32_e32 vcc, 0, v54
	v_mov_b32_e32 v78, 0
	v_mov_b32_e32 v150, 0
	s_and_saveexec_b64 s[14:15], vcc
	s_cbranch_execz .LBB0_1424
	v_mov_b32_e32 v2, v54
	v_lshl_add_u64 v[62:63], v[2:3], 1, s[16:17]
	global_load_ushort v150, v[62:63], off offset:-2
.LBB0_1424:
	s_or_b64 exec, exec, s[14:15]
	v_add_u32_e32 v62, 0x1008, v52
	v_cmp_gt_i32_e32 vcc, s52, v62
	s_and_saveexec_b64 s[14:15], vcc
	s_cbranch_execz .LBB0_1426
	v_ashrrev_i32_e32 v63, 31, v62
	v_lshl_add_u64 v[62:63], v[62:63], 1, s[16:17]
	global_load_ushort v78, v[62:63], off

.LBB0_1427:
	v_writelane_b32 v251, s12, 62
	v_writelane_b32 v251, s6, 63
	s_nop 1
	v_writelane_b32 v255, s7, 0
	s_or_b64 exec, exec, s[26:27]
	s_waitcnt vmcnt(0)
	v_cvt_f32_f16_e32 v64, v64
	v_cvt_f32_f16_e32 v65, v65
	v_cvt_f32_f16_e32 v82, v82
	v_cvt_f32_f16_e32 v90, v90
	v_cvt_f32_f16_e32 v67, v67
	v_cvt_f32_f16_e32 v80, v80
	v_cvt_f32_f16_e32 v99, v99
	v_cvt_f32_f16_e32 v98, v98
	v_cvt_f32_f16_e32 v113, v113
	v_cvt_f32_f16_e32 v112, v112
	v_cvt_f32_f16_e32 v103, v103
	v_cvt_f32_f16_e32 v102, v102
	v_cvt_f32_f16_e32 v115, v115
	v_cvt_f32_f16_e32 v114, v114
	v_cvt_f32_f16_e32 v157, v157
	v_cvt_f32_f16_e32 v106, v106
	v_cvt_f32_f16_e32 v93, v93
	v_cvt_f32_f16_e32 v92, v92
	v_cvt_f32_f16_e32 v149, v149
	v_cvt_f32_f16_e32 v58, v58
	v_cvt_f32_f16_e32 v95, v95
	v_cvt_f32_f16_e32 v94, v94
	v_cvt_f32_f16_e32 v150, v150
	v_cvt_f32_f16_e32 v78, v78
	v_cvt_f32_f16_e32 v2, v40
	v_cvt_f32_f16_sdwa v63, v40 dst_sel:DWORD dst_unused:UNUSED_PAD src0_sel:WORD_1
	v_cvt_f32_f16_e32 v68, v41
	v_cvt_f32_f16_sdwa v111, v48 dst_sel:DWORD dst_unused:UNUSED_PAD src0_sel:WORD_1
	s_waitcnt lgkmcnt(0)
	v_mul_f32_e32 v62, v83, v2
	v_mul_f32_e32 v2, v89, v2
	v_fma_mix_f32 v2, v83, v40, v2 op_sel:[0,1,0] op_sel_hi:[0,1,0]
	v_fmac_f32_e32 v62, v89, v64
	v_fma_mix_f32 v2, v85, v41, v2 op_sel_hi:[0,1,0]
	v_fma_mix_f32 v62, v85, v40, v62 op_sel:[0,1,0] op_sel_hi:[0,1,0]
	v_add_f32_e32 v64, v87, v2
	v_cvt_f32_f16_sdwa v2, v41 dst_sel:DWORD dst_unused:UNUSED_PAD src0_sel:WORD_1
	v_mul_f32_e32 v40, v89, v63
	v_fma_mix_f32 v40, v83, v41, v40 op_sel_hi:[0,1,0]
	v_fma_mix_f32 v40, v85, v41, v40 op_sel:[0,1,0] op_sel_hi:[0,1,0]
	v_add_f32_e32 v66, v87, v40
	v_cvt_f32_f16_e32 v40, v42
	v_mul_f32_e32 v63, v89, v68
	v_fma_mix_f32 v41, v83, v41, v63 op_sel:[0,1,0] op_sel_hi:[0,1,0]
	v_mul_f32_e32 v2, v89, v2
	v_fma_mix_f32 v41, v85, v42, v41 op_sel_hi:[0,1,0]
	v_fma_mix_f32 v2, v83, v42, v2 op_sel_hi:[0,1,0]
	v_add_f32_e32 v68, v87, v41
	v_cvt_f32_f16_sdwa v41, v42 dst_sel:DWORD dst_unused:UNUSED_PAD src0_sel:WORD_1
	v_fma_mix_f32 v2, v85, v42, v2 op_sel:[0,1,0] op_sel_hi:[0,1,0]
	v_add_f32_e32 v70, v87, v2
	v_cvt_f32_f16_e32 v2, v43
	v_mul_f32_e32 v40, v89, v40
	v_fma_mix_f32 v40, v83, v42, v40 op_sel:[0,1,0] op_sel_hi:[0,1,0]
	v_fma_mix_f32 v40, v85, v43, v40 op_sel_hi:[0,1,0]
	v_cvt_f32_f16_e32 v110, v48
	v_add_f32_e32 v72, v87, v40
	v_mul_f32_e32 v40, v89, v41
	v_fma_mix_f32 v40, v83, v43, v40 op_sel_hi:[0,1,0]
	v_mul_f32_e32 v2, v89, v2
	v_cvt_f32_f16_e32 v42, v49
	v_fma_mix_f32 v40, v85, v43, v40 op_sel:[0,1,0] op_sel_hi:[0,1,0]
	v_fma_mix_f32 v2, v83, v43, v2 op_sel:[0,1,0] op_sel_hi:[0,1,0]
	v_add_f32_e32 v74, v87, v40
	v_fmac_f32_e32 v2, v85, v65
	v_pk_mul_f32 v[40:41], v[96:97], v[110:111]
	v_add_f32_e32 v76, v87, v2
	v_fma_f32 v2, v91, v67, v40
	v_cvt_f32_f16_sdwa v43, v49 dst_sel:DWORD dst_unused:UNUSED_PAD src0_sel:WORD_1
	v_add_f32_e32 v2, v41, v2
	v_mov_b32_e32 v40, v97
	v_mov_b32_e32 v41, v96
	v_mov_b32_e32 v110, v42
	v_pk_mul_f32 v[110:111], v[40:41], v[110:111]
	v_add_f32_e32 v63, v108, v2
	v_fma_mix_f32 v2, v91, v48, v111 op_sel_hi:[0,1,0]
	v_add_f32_e32 v2, v110, v2
	v_pk_mul_f32 v[110:111], v[96:97], v[42:43]
	v_add_f32_e32 v65, v108, v2
	v_fma_mix_f32 v2, v91, v48, v110 op_sel:[0,1,0] op_sel_hi:[0,1,0]
	v_cvt_f32_f16_e32 v110, v50
	v_add_f32_e32 v2, v111, v2
	v_cvt_f32_f16_sdwa v111, v50 dst_sel:DWORD dst_unused:UNUSED_PAD src0_sel:WORD_1
	v_add_f32_e32 v67, v108, v2
	v_mov_b32_e32 v42, v110
	v_pk_mul_f32 v[42:43], v[40:41], v[42:43]
	v_writelane_b32 v255, s18, 1
	v_fma_mix_f32 v2, v91, v49, v43 op_sel_hi:[0,1,0]
	v_add_f32_e32 v2, v42, v2
	v_pk_mul_f32 v[42:43], v[96:97], v[110:111]
	v_add_f32_e32 v69, v108, v2
	v_fma_mix_f32 v2, v91, v49, v42 op_sel:[0,1,0] op_sel_hi:[0,1,0]
	v_cvt_f32_f16_e32 v42, v51
	v_add_f32_e32 v2, v43, v2
	v_cvt_f32_f16_sdwa v43, v51 dst_sel:DWORD dst_unused:UNUSED_PAD src0_sel:WORD_1
	v_add_f32_e32 v71, v108, v2
	v_mov_b32_e32 v110, v42
	v_pk_mul_f32 v[48:49], v[40:41], v[110:111]
	v_mov_b32_e32 v81, v43
	v_fma_mix_f32 v2, v91, v50, v49 op_sel_hi:[0,1,0]
	v_add_f32_e32 v2, v48, v2
	v_pk_mul_f32 v[48:49], v[96:97], v[42:43]
	v_add_f32_e32 v73, v108, v2
	v_fma_mix_f32 v2, v91, v50, v48 op_sel:[0,1,0] op_sel_hi:[0,1,0]
	v_add_f32_e32 v2, v49, v2
	v_pk_mul_f32 v[42:43], v[40:41], v[80:81]
	v_add_f32_e32 v75, v108, v2
	v_fma_mix_f32 v2, v91, v51, v43 op_sel_hi:[0,1,0]
	v_add_f32_e32 v2, v42, v2
	v_add_f32_e32 v77, v108, v2
	s_and_b64 s[4:5], s[18:19], exec
	v_ashrrev_i32_e32 v2, 5, v52
	v_add_f32_e32 v62, v87, v62
	v_writelane_b32 v255, s19, 2
	s_cselect_b32 s50, 14, 9
	v_lshlrev_b32_e32 v151, 3, v52
	v_lshlrev_b32_e32 v153, 3, v2
	s_barrier
	s_and_saveexec_b64 s[14:15], s[34:35]
	s_cbranch_execz .LBB0_1429
	v_add3_u32 v2, 0, v151, v153
	ds_write2_b64 v2, v[62:63], v[64:65] offset1:1
	ds_write2_b64 v2, v[66:67], v[68:69] offset0:2 offset1:3
	ds_write2_b64 v2, v[70:71], v[72:73] offset0:4 offset1:5
	ds_write2_b64 v2, v[74:75], v[76:77] offset0:6 offset1:7
